# speedup vs baseline: 1.1268x; 1.0125x over previous
.LBB0_297:
	s_setprio 3
	s_xor_b32 s0, s98, 1
	s_mulk_i32 s0, 0x4800
	v_lshl_or_b32 v0, v126, 1, s0
	v_add_u32_e32 v2, s0, v204
	v_add_u32_e32 v3, v0, v216
	s_waitcnt vmcnt(3)
	ds_write_b128 v3, v[8:11]
	v_lshl_add_u32 v3, v217, 1, v2
	v_add_u32_e32 v0, v0, v219
	s_waitcnt vmcnt(2)
	ds_write_b16 v3, v4 offset:9216
	ds_write_b16_d16_hi v3, v4 offset:9360
	ds_write_b16 v3, v5 offset:9504
	ds_write_b16_d16_hi v3, v5 offset:9648
	ds_write_b16 v3, v6 offset:9792
	ds_write_b16_d16_hi v3, v6 offset:9936
	ds_write_b16 v3, v7 offset:10080
	ds_write_b16_d16_hi v3, v7 offset:10224
	s_waitcnt vmcnt(1)
	ds_write_b128 v0, v[12:15]
	v_lshl_add_u32 v0, v220, 1, v2
	s_and_b64 vcc, exec, s[54:55]
	s_add_i32 s99, s97, 1
	s_waitcnt vmcnt(0)
	ds_write_b16 v0, v16 offset:9216
	ds_write_b16_d16_hi v0, v16 offset:9360
	ds_write_b16 v0, v17 offset:9504
	ds_write_b16_d16_hi v0, v17 offset:9648
	ds_write_b16 v0, v18 offset:9792
	ds_write_b16_d16_hi v0, v18 offset:9936
	ds_write_b16 v0, v19 offset:10080
	ds_write_b16_d16_hi v0, v19 offset:10224
	s_cbranch_vccnz .LBB0_310
	s_ashr_i32 s6, s99, 5
	s_cmp_gt_i32 s6, 3
	s_movk_i32 s0, 0x80
	s_cbranch_scc1 .LBB0_309
	s_lshl_b32 s7, s6, 2
	v_mov_b32_e32 v0, s7
	ds_read_b32 v0, v0 offset:54272
	s_lshl_b32 s0, -1, s99
	s_waitcnt lgkmcnt(0)
	v_readfirstlane_b32 s8, v0
	s_and_b32 s0, s8, s0
	s_cmp_lg_u32 s0, 0
	s_cbranch_scc0 .LBB0_301
	s_and_b32 s6, s99, 0xffffffe0
	s_ff1_i32_b32 s0, s0
	s_or_b32 s0, s0, s6
	s_branch .LBB0_309

.LBB0_312:
	s_setprio 0
	s_mul_i32 s78, s98, 0x4800
	v_or_b32_e32 v0, s78, v205
	v_add_u32_e32 v2, v0, v207
	ds_read_b128 v[60:63], v2
	ds_read_b128 v[64:67], v2 offset:64
	v_add_u32_e32 v0, v0, v222
	ds_read_b128 v[72:75], v0
	ds_read_b128 v[92:95], v0 offset:64
	ds_read_b128 v[100:103], v2 offset:4608
	ds_read_b128 v[104:107], v2 offset:4672
	ds_read_b128 v[112:115], v2 offset:6912
	ds_read_b128 v[156:159], v2 offset:6976
	s_waitcnt vmcnt(3) lgkmcnt(5)
	s_setprio 2
	v_mfma_f32_16x16x32_bf16 v[96:99], v[72:75], v[20:23], 0
	s_cmp_eq_u32 s74, s85
	s_cselect_b64 s[6:7], -1, 0
	s_or_b64 s[6:7], s[18:19], s[6:7]
	v_mfma_f32_16x16x32_bf16 v[68:71], v[60:63], v[20:23], 0
	s_lshl_b32 s0, s74, 6
	s_cmp_lt_i32 s0, s94
	s_cselect_b64 s[8:9], -1, 0
	s_waitcnt lgkmcnt(3)
	v_mfma_f32_16x16x32_bf16 v[108:111], v[100:103], v[20:23], 0
	s_and_b64 s[8:9], s[68:69], s[8:9]
	s_or_b64 s[64:65], s[6:7], s[8:9]
	v_or_b32_e32 v245, s0, v206
	s_waitcnt lgkmcnt(1)
	v_mfma_f32_16x16x32_bf16 v[160:163], v[112:115], v[20:23], 0
	s_and_b64 vcc, exec, s[64:65]
	s_waitcnt vmcnt(1)
	v_mfma_f32_16x16x32_bf16 v[60:63], v[60:63], v[28:31], 0
	v_mfma_f32_16x16x32_bf16 v[164:167], v[72:75], v[28:31], 0
	v_mfma_f32_16x16x32_bf16 v[100:103], v[100:103], v[28:31], 0
	v_mfma_f32_16x16x32_bf16 v[196:199], v[112:115], v[28:31], 0
	v_mfma_f32_16x16x32_bf16 v[120:123], v[64:67], v[24:27], v[68:71]
	v_mfma_f32_16x16x32_bf16 v[116:119], v[92:95], v[24:27], v[96:99]
	v_mfma_f32_16x16x32_bf16 v[112:115], v[104:107], v[24:27], v[108:111]
	s_waitcnt lgkmcnt(0)
	v_mfma_f32_16x16x32_bf16 v[108:111], v[156:159], v[24:27], v[160:163]
	s_waitcnt vmcnt(0)
	v_mfma_f32_16x16x32_bf16 v[72:75], v[64:67], v[32:35], v[60:63]
	v_mfma_f32_16x16x32_bf16 v[68:71], v[92:95], v[32:35], v[164:167]
	v_mfma_f32_16x16x32_bf16 v[64:67], v[104:107], v[32:35], v[100:103]
	v_mfma_f32_16x16x32_bf16 v[60:63], v[156:159], v[32:35], v[196:199]
	s_setprio 0
	s_cbranch_vccz .LBB0_474
	v_add_u32_e32 v92, -1, v237
	s_orn2_b64 s[6:7], s[14:15], s[12:13]
	v_add_u32_e32 v93, 1, v239
	v_mov_b32_e32 v94, 0x80000001
	v_cndmask_b32_e64 v92, v92, v236, s[12:13]
	v_cndmask_b32_e64 v93, v93, v94, s[6:7]
	v_sub_u32_e32 v92, v92, v93
	v_sub_u32_e32 v93, v245, v93
	v_add_u32_e32 v94, 0, v93
	v_cmp_gt_u32_e32 vcc, v94, v92
	v_add_u32_e32 v95, 1, v93
	v_cmp_gt_u32_e64 s[8:9], v95, v92
	v_add_u32_e32 v0, 2, v93
	v_cmp_gt_u32_e64 s[10:11], v0, v92
	v_cndmask_b32_e32 v120, v120, v193, vcc
	v_add_u32_e32 v94, 3, v93
	v_cmp_gt_u32_e32 vcc, v94, v92
	v_cndmask_b32_e64 v121, v121, v193, s[8:9]
	v_add_u32_e32 v95, 16, v93
	v_cmp_gt_u32_e64 s[8:9], v95, v92
	v_cndmask_b32_e64 v122, v122, v193, s[10:11]
	v_add_u32_e32 v0, 17, v93
	v_cmp_gt_u32_e64 s[10:11], v0, v92
	v_cndmask_b32_e32 v123, v123, v193, vcc
	v_add_u32_e32 v94, 18, v93
	v_cmp_gt_u32_e32 vcc, v94, v92
	v_cndmask_b32_e64 v116, v116, v193, s[8:9]
	v_add_u32_e32 v95, 19, v93
	v_cmp_gt_u32_e64 s[8:9], v95, v92
	v_cndmask_b32_e64 v117, v117, v193, s[10:11]
	v_add_u32_e32 v0, 32, v93
	v_cmp_gt_u32_e64 s[10:11], v0, v92
	v_cndmask_b32_e32 v118, v118, v193, vcc
	v_add_u32_e32 v94, 33, v93
	v_cmp_gt_u32_e32 vcc, v94, v92
	v_cndmask_b32_e64 v119, v119, v193, s[8:9]
	v_add_u32_e32 v95, 34, v93
	v_cmp_gt_u32_e64 s[8:9], v95, v92
	v_cndmask_b32_e64 v112, v112, v193, s[10:11]
	v_add_u32_e32 v0, 35, v93
	v_cmp_gt_u32_e64 s[10:11], v0, v92
	v_cndmask_b32_e32 v113, v113, v193, vcc
	v_add_u32_e32 v94, 48, v93
	v_cmp_gt_u32_e32 vcc, v94, v92
	v_cndmask_b32_e64 v114, v114, v193, s[8:9]
	v_add_u32_e32 v95, 49, v93
	v_cmp_gt_u32_e64 s[8:9], v95, v92
	v_cndmask_b32_e64 v115, v115, v193, s[10:11]
	v_add_u32_e32 v0, 50, v93
	v_cmp_gt_u32_e64 s[10:11], v0, v92
	v_cndmask_b32_e32 v108, v108, v193, vcc
	v_add_u32_e32 v94, 51, v93
	v_cmp_gt_u32_e32 vcc, v94, v92
	v_cndmask_b32_e64 v109, v109, v193, s[8:9]
	v_cndmask_b32_e64 v110, v110, v193, s[10:11]
	v_cndmask_b32_e32 v111, v111, v193, vcc

.LBB0_486:
	v_add3_u32 v0, s78, v207, v235
	v_cvt_pk_bf16_f32 v44, v2, v3
	v_add_u32_e32 v2, 0x2000, v0
	ds_read2_b64 v[52:55], v2 offset0:128 offset1:132
	v_add_u32_e32 v3, 0x2800, v0
	ds_read2_b64 v[68:71], v3 offset0:160 offset1:164
	v_cvt_pk_bf16_f32 v45, v156, v157
	v_cvt_pk_bf16_f32 v46, v158, v159
	v_cvt_pk_bf16_f32 v47, v160, v161
	v_cvt_pk_bf16_f32 v48, v84, v85
	s_waitcnt lgkmcnt(0)
	v_mov_b32_e32 v72, v68
	v_mov_b32_e32 v73, v69
	s_setprio 2
	v_mfma_f32_16x16x32_bf16 v[56:59], v[52:55], v[44:47], v[104:107]
	v_cvt_pk_bf16_f32 v49, v86, v87
	v_cvt_pk_bf16_f32 v50, v88, v89
	v_cvt_pk_bf16_f32 v51, v90, v91
	v_add_u32_e32 v104, 0x3000, v0
	v_add_u32_e32 v0, 0x3800, v0
	ds_read2_b64 v[84:87], v0 offset0:232 offset1:236
	v_mfma_f32_16x16x32_bf16 v[52:55], v[52:55], v[48:51], v[80:83]
	v_cvt_pk_bf16_f32 v60, v162, v163
	v_cvt_pk_bf16_f32 v61, v164, v165
	v_cvt_pk_bf16_f32 v62, v166, v167
	v_mfma_f32_16x16x32_bf16 v[80:83], v[70:73], v[44:47], v[92:95]
	s_waitcnt lgkmcnt(0)
	v_mov_b32_e32 v88, v84
	v_mov_b32_e32 v89, v85
	v_cvt_pk_bf16_f32 v63, v168, v169
	v_mfma_f32_16x16x32_bf16 v[68:71], v[70:73], v[48:51], v[76:79]
	ds_read2_b64 v[72:75], v104 offset0:200 offset1:204
	v_cvt_pk_bf16_f32 v64, v116, v117
	v_cvt_pk_bf16_f32 v65, v118, v119
	s_waitcnt lgkmcnt(0)
	v_mfma_f32_16x16x32_bf16 v[76:79], v[72:75], v[44:47], v[100:103]
	v_cvt_pk_bf16_f32 v66, v120, v121
	v_cvt_pk_bf16_f32 v67, v122, v123
	v_mfma_f32_16x16x32_bf16 v[72:75], v[72:75], v[48:51], v[112:115]
	v_mfma_f32_16x16x32_bf16 v[92:95], v[86:89], v[48:51], v[108:111]
	ds_read2_b64 v[48:51], v2 offset0:136 offset1:140
	v_mfma_f32_16x16x32_bf16 v[44:47], v[86:89], v[44:47], v[96:99]
	s_waitcnt lgkmcnt(0)
	v_mfma_f32_16x16x32_bf16 v[88:91], v[48:51], v[60:63], v[56:59]
	v_mfma_f32_16x16x32_bf16 v[56:59], v[48:51], v[64:67], v[52:55]
	ds_read2_b64 v[48:51], v3 offset0:168 offset1:172
	s_waitcnt lgkmcnt(0)
	s_nop 0
	v_mov_b32_e32 v52, v48
	v_mov_b32_e32 v53, v49
	s_nop 1
	v_mfma_f32_16x16x32_bf16 v[84:87], v[50:53], v[60:63], v[80:83]
	v_mfma_f32_16x16x32_bf16 v[52:55], v[50:53], v[64:67], v[68:71]
	ds_read2_b64 v[48:51], v104 offset0:192 offset1:196
	s_nop 1
	ds_read2_b64 v[68:71], v0 offset0:224 offset1:228
	s_waitcnt lgkmcnt(1)
	v_mfma_f32_16x16x32_bf16 v[80:83], v[48:51], v[60:63], v[76:79]
	v_mfma_f32_16x16x32_bf16 v[48:51], v[48:51], v[64:67], v[72:75]
	s_waitcnt lgkmcnt(0)
	s_nop 1
	v_mov_b32_e32 v72, v68
	v_mov_b32_e32 v73, v69
	s_nop 1
	v_mfma_f32_16x16x32_bf16 v[76:79], v[70:73], v[60:63], v[44:47]
	v_mfma_f32_16x16x32_bf16 v[44:47], v[70:73], v[64:67], v[92:95]
	s_setprio 0
	s_branch .LBB0_669

.LBB0_745:
	s_setprio 3
	s_add_i32 s6, s2, -2
	s_and_b32 s9, s6, 1
	s_add_i32 s8, s2, -1
	s_cmp_ge_i32 s8, s0
	s_cbranch_scc1 .LBB0_748
	s_xor_b32 s7, s9, 1
	s_mulk_i32 s7, 0x4800
	v_lshl_or_b32 v66, v102, 1, s7
	v_add_u32_e32 v67, s7, v131
	v_add_u32_e32 v68, v66, v134
	s_waitcnt vmcnt(3)
	ds_write_b128 v68, v[10:13]
	v_lshl_add_u32 v68, v135, 1, v67
	v_add_u32_e32 v66, v66, v137
	s_waitcnt vmcnt(2)
	ds_write_b16 v68, v22 offset:9216
	ds_write_b16_d16_hi v68, v22 offset:9360
	ds_write_b16 v68, v23 offset:9504
	ds_write_b16_d16_hi v68, v23 offset:9648
	ds_write_b16 v68, v24 offset:9792
	ds_write_b16_d16_hi v68, v24 offset:9936
	ds_write_b16 v68, v25 offset:10080
	ds_write_b16_d16_hi v68, v25 offset:10224
	s_waitcnt vmcnt(1)
	ds_write_b128 v66, v[26:29]
	v_lshl_add_u32 v66, v138, 1, v67
	s_cmp_ge_i32 s2, s0
	s_waitcnt vmcnt(0)
	ds_write_b16 v66, v30 offset:9216
	ds_write_b16_d16_hi v66, v30 offset:9360
	ds_write_b16 v66, v31 offset:9504
	ds_write_b16_d16_hi v66, v31 offset:9648
	ds_write_b16 v66, v32 offset:9792
	ds_write_b16_d16_hi v66, v32 offset:9936
	ds_write_b16 v66, v33 offset:10080
	ds_write_b16_d16_hi v66, v33 offset:10224
	s_cbranch_scc1 .LBB0_748
	s_movk_i32 s7, 0x1800
	v_mad_i64_i32 v[10:11], s[10:11], v145, s7, v[122:123]
	s_mov_b64 s[12:13], 0x800
	v_mad_i64_i32 v[26:27], s[10:11], v146, s7, v[122:123]
	v_lshl_add_u64 v[22:23], v[10:11], 0, s[12:13]
	v_lshl_add_u64 v[30:31], v[26:27], 0, s[12:13]
	global_load_dwordx4 v[10:13], v[10:11], off offset:2048
	s_nop 0
	global_load_dwordx4 v[22:25], v[22:23], off offset:2048
	s_nop 0
	global_load_dwordx4 v[26:29], v[26:27], off offset:2048
	s_nop 0
	global_load_dwordx4 v[30:33], v[30:31], off offset:2048
	s_movk_i32 s39, 0x1800
.LBB0_748:
	s_setprio 0
	s_lshr_b32 s13, s6, 2
	s_and_b32 s12, s6, 3
	s_cmp_eq_u32 s13, s38
	s_cselect_b64 s[10:11], -1, 0
	s_cmp_lg_u32 s13, s38
	s_cselect_b64 s[6:7], -1, 0
	v_cmp_le_i32_e32 vcc, s12, v117
	s_or_b64 s[14:15], s[6:7], vcc
	v_mov_b32_e32 v66, v126
	v_mov_b32_e32 v67, v127
	s_and_saveexec_b64 s[6:7], s[14:15]
	s_cbranch_execz .LBB0_761
	s_lshl_b32 s13, 1, s13
	v_and_b32_e32 v66, s13, v120
	v_cmp_ne_u32_e32 vcc, 0, v66
	v_and_b32_e32 v66, s13, v121
	s_or_b64 s[96:97], s[10:11], vcc
	v_cmp_ne_u32_e64 s[98:99], 0, v66
	s_or_b64 s[14:15], s[96:97], s[98:99]
	v_cndmask_b32_e64 v66, 0, 1, s[14:15]
	v_cmp_ne_u32_e32 vcc, 0, v66
	s_cbranch_vccz .LBB0_759
	s_mulk_i32 s9, 0x4800
	v_or_b32_e32 v66, s9, v132
	v_add_u32_e32 v147, v66, v133
	ds_read_b128 v[66:69], v147
	ds_read_b128 v[82:85], v147 offset:64
	ds_read_b128 v[74:77], v147 offset:2304
	ds_read_b128 v[86:89], v147 offset:2368
	ds_read_b128 v[90:93], v147 offset:4608
	ds_read_b128 v[148:151], v147 offset:4672
	ds_read_b128 v[152:155], v147 offset:6912
	ds_read_b128 v[156:159], v147 offset:6976
	s_waitcnt vmcnt(3) lgkmcnt(7)
	s_setprio 2
	v_mfma_f32_16x16x32_bf16 v[70:73], v[66:69], v[2:5], 0
	v_cmp_eq_u32_e32 vcc, s12, v117
	s_and_b64 s[12:13], s[10:11], vcc
	s_waitcnt lgkmcnt(5)
	v_mfma_f32_16x16x32_bf16 v[78:81], v[74:77], v[2:5], 0
	s_waitcnt lgkmcnt(3)
	v_mfma_f32_16x16x32_bf16 v[94:97], v[90:93], v[2:5], 0
	s_waitcnt lgkmcnt(1)
	v_mfma_f32_16x16x32_bf16 v[160:163], v[152:155], v[2:5], 0
	s_waitcnt vmcnt(1)
	v_mfma_f32_16x16x32_bf16 v[164:167], v[66:69], v[14:17], 0
	v_mfma_f32_16x16x32_bf16 v[204:207], v[74:77], v[14:17], 0
	v_mfma_f32_16x16x32_bf16 v[208:211], v[90:93], v[14:17], 0
	v_mfma_f32_16x16x32_bf16 v[152:155], v[152:155], v[14:17], 0
	v_mfma_f32_16x16x32_bf16 v[74:77], v[82:85], v[6:9], v[70:73]
	v_mfma_f32_16x16x32_bf16 v[70:73], v[86:89], v[6:9], v[78:81]
	v_mfma_f32_16x16x32_bf16 v[66:69], v[148:151], v[6:9], v[94:97]
	s_waitcnt lgkmcnt(0)
	v_mfma_f32_16x16x32_bf16 v[78:81], v[156:159], v[6:9], v[160:163]
	s_waitcnt vmcnt(0)
	v_mfma_f32_16x16x32_bf16 v[94:97], v[82:85], v[18:21], v[164:167]
	v_mfma_f32_16x16x32_bf16 v[90:93], v[86:89], v[18:21], v[204:207]
	v_mfma_f32_16x16x32_bf16 v[86:89], v[148:151], v[18:21], v[208:211]
	v_mfma_f32_16x16x32_bf16 v[82:85], v[156:159], v[18:21], v[152:155]
	s_setprio 0
	s_and_saveexec_b64 s[14:15], s[12:13]
	s_cbranch_execz .LBB0_752
	s_nop 0
	v_mov_b32_e32 v78, s43
	v_cndmask_b32_e64 v78, v74, v78, s[50:51]
	v_cndmask_b32_e64 v74, v78, v74, s[52:53]
	v_mov_b32_e32 v78, s43
	v_cndmask_b32_e64 v70, v70, v78, s[58:59]
	v_cndmask_b32_e64 v66, v66, v78, s[66:67]
	v_mov_b32_e32 v78, 0xf149f2ca
	v_cndmask_b32_e64 v75, v193, v75, s[52:53]
	v_cndmask_b32_e64 v76, v76, v193, s[54:55]
	v_cndmask_b32_e64 v77, v77, v193, s[56:57]
	v_cndmask_b32_e64 v71, v71, v193, s[60:61]
	v_cndmask_b32_e64 v72, v72, v193, s[62:63]
	v_cndmask_b32_e64 v73, v73, v193, s[64:65]
	v_cndmask_b32_e64 v67, v67, v193, s[68:69]
	v_cndmask_b32_e64 v68, v68, v193, s[70:71]
	v_cndmask_b32_e64 v69, v69, v193, s[72:73]
	v_mov_b32_e32 v79, v78
	v_mov_b32_e32 v80, v78
	v_mov_b32_e32 v81, v78

.LBB0_758:
	v_cndmask_b32_e64 v149, v193, -v148, s[10:11]
	v_fmamk_f32 v94, v94, 0x3e38aa3b, v149
	v_exp_f32_e32 v94, v94
	v_fmamk_f32 v95, v95, 0x3e38aa3b, v149
	v_exp_f32_e32 v95, v95
	v_fmamk_f32 v96, v96, 0x3e38aa3b, v149
	v_exp_f32_e32 v96, v96
	v_fmamk_f32 v97, v97, 0x3e38aa3b, v149
	v_exp_f32_e32 v97, v97
	v_fmamk_f32 v90, v90, 0x3e38aa3b, v149
	v_add_f32_e32 v150, 0, v94
	v_exp_f32_e32 v90, v90
	v_fmamk_f32 v91, v91, 0x3e38aa3b, v149
	v_add_f32_e32 v150, v95, v150
	v_exp_f32_e32 v91, v91
	v_fmamk_f32 v92, v92, 0x3e38aa3b, v149
	v_add_f32_e32 v150, v96, v150
	v_exp_f32_e32 v92, v92
	v_fmamk_f32 v93, v93, 0x3e38aa3b, v149
	v_add_f32_e32 v150, v97, v150
	v_exp_f32_e32 v93, v93
	v_fmamk_f32 v86, v86, 0x3e38aa3b, v149
	v_add_f32_e32 v150, v90, v150
	v_exp_f32_e32 v86, v86
	v_fmamk_f32 v87, v87, 0x3e38aa3b, v149
	v_add_f32_e32 v150, v91, v150
	v_exp_f32_e32 v87, v87
	v_fmamk_f32 v88, v88, 0x3e38aa3b, v149
	v_add_f32_e32 v150, v92, v150
	v_exp_f32_e32 v88, v88
	v_fmamk_f32 v89, v89, 0x3e38aa3b, v149
	v_add_f32_e32 v150, v93, v150
	v_exp_f32_e32 v89, v89
	v_fmamk_f32 v82, v82, 0x3e38aa3b, v149
	v_add_f32_e32 v150, v86, v150
	v_exp_f32_e32 v151, v82
	v_add_f32_e32 v150, v87, v150
	v_add_f32_e32 v150, v88, v150
	v_add_f32_e32 v150, v89, v150
	v_fmamk_f32 v83, v83, 0x3e38aa3b, v149
	v_add_f32_e32 v82, v151, v150
	v_exp_f32_e32 v150, v83
	v_fmamk_f32 v83, v84, 0x3e38aa3b, v149
	v_exp_f32_e32 v84, v83
	v_fmac_f32_e32 v149, 0x3e38aa3b, v85
	v_exp_f32_e32 v85, v149
	v_cndmask_b32_e64 v83, v193, -v147, s[96:97]
	v_add_f32_e32 v82, v150, v82
	v_fmamk_f32 v66, v66, 0x3e38aa3b, v83
	v_add_f32_e32 v82, v84, v82
	v_exp_f32_e32 v153, v66
	v_fmamk_f32 v66, v67, 0x3e38aa3b, v83
	v_add_f32_e32 v82, v85, v82
	v_fmamk_f32 v74, v74, 0x3e38aa3b, v83
	v_exp_f32_e32 v154, v66
	v_fmamk_f32 v66, v68, 0x3e38aa3b, v83
	v_fmac_f32_e32 v82, v126, v130
	v_exp_f32_e32 v126, v74
	v_fmamk_f32 v74, v75, 0x3e38aa3b, v83
	v_exp_f32_e32 v155, v66
	v_fmamk_f32 v66, v69, 0x3e38aa3b, v83
	v_exp_f32_e32 v130, v74
	v_fmamk_f32 v74, v76, 0x3e38aa3b, v83
	v_exp_f32_e32 v156, v66
	v_fmamk_f32 v66, v78, 0x3e38aa3b, v83
	v_exp_f32_e32 v149, v74
	v_fmamk_f32 v74, v77, 0x3e38aa3b, v83
	v_exp_f32_e32 v78, v66
	v_fmamk_f32 v66, v79, 0x3e38aa3b, v83
	v_exp_f32_e32 v152, v74
	v_fmamk_f32 v70, v70, 0x3e38aa3b, v83
	v_fmamk_f32 v71, v71, 0x3e38aa3b, v83
	v_fmamk_f32 v72, v72, 0x3e38aa3b, v83
	v_fmamk_f32 v73, v73, 0x3e38aa3b, v83
	v_exp_f32_e32 v79, v66
	v_fmamk_f32 v66, v80, 0x3e38aa3b, v83
	v_fmac_f32_e32 v83, 0x3e38aa3b, v81
	v_exp_f32_e32 v70, v70
	v_exp_f32_e32 v71, v71
	v_exp_f32_e32 v81, v83
	v_add_f32_e32 v83, 0, v126
	v_add_f32_e32 v83, v130, v83
	v_exp_f32_e32 v72, v72
	v_add_f32_e32 v83, v149, v83
	v_exp_f32_e32 v73, v73
	v_add_f32_e32 v83, v152, v83
	v_cvt_pk_bf16_f32 v76, v70, v71
	v_add_f32_e32 v70, v70, v83
	v_add_f32_e32 v70, v71, v70
	v_add_f32_e32 v70, v72, v70
	v_add_f32_e32 v70, v73, v70
	v_add_f32_e32 v70, v153, v70
	v_add_f32_e32 v70, v154, v70
	v_exp_f32_e32 v80, v66
	v_add_f32_e32 v70, v155, v70
	v_add_f32_e32 v70, v156, v70
	v_add_f32_e32 v70, v78, v70
	v_add_f32_e32 v70, v79, v70
	v_cvt_pk_bf16_f32 v69, v80, v81
	v_add_f32_e32 v70, v80, v70
	v_cvt_pk_bf16_f32 v80, v90, v91
	v_add3_u32 v90, s9, v133, v143
	v_add_u32_e32 v91, 0x2000, v90
	v_cvt_pk_bf16_f32 v77, v72, v73
	v_add_f32_e32 v83, v81, v70
	v_cvt_pk_bf16_f32 v70, v86, v87
	v_cvt_pk_bf16_f32 v73, v84, v85
	ds_read2_b64 v[84:87], v91 offset0:128 offset1:132
	v_cvt_pk_bf16_f32 v74, v126, v130
	v_cvt_pk_bf16_f32 v75, v149, v152
	v_cvt_pk_bf16_f32 v68, v78, v79
	v_cvt_pk_bf16_f32 v78, v94, v95
	v_cvt_pk_bf16_f32 v79, v96, v97
	v_cvt_pk_bf16_f32 v81, v92, v93
	v_add_u32_e32 v92, 0x2800, v90
	s_waitcnt lgkmcnt(0)
	s_setprio 2
	v_mfma_f32_16x16x32_bf16 v[62:65], v[84:87], v[74:77], v[62:65]
	v_cvt_pk_bf16_f32 v71, v88, v89
	v_add_u32_e32 v93, 0x3000, v90
	v_add_u32_e32 v90, 0x3800, v90
	v_mfma_f32_16x16x32_bf16 v[46:49], v[84:87], v[78:81], v[46:49]
	ds_read2_b64 v[84:87], v92 offset0:160 offset1:164
	v_cvt_pk_bf16_f32 v66, v153, v154
	v_cvt_pk_bf16_f32 v67, v155, v156
	v_cvt_pk_bf16_f32 v72, v151, v150
	v_fmac_f32_e32 v83, v127, v128
	s_waitcnt lgkmcnt(0)
	v_mov_b32_e32 v88, v84
	v_mov_b32_e32 v89, v85
	v_mov_b32_e32 v127, v83
	v_mov_b32_e32 v126, v82
	v_mfma_f32_16x16x32_bf16 v[50:53], v[86:89], v[74:77], v[50:53]
	v_mov_b32_e32 v130, v148
	v_mov_b32_e32 v128, v147
	v_mfma_f32_16x16x32_bf16 v[42:45], v[86:89], v[78:81], v[42:45]
	ds_read2_b64 v[84:87], v93 offset0:200 offset1:204
	s_waitcnt lgkmcnt(0)
	v_mfma_f32_16x16x32_bf16 v[58:61], v[84:87], v[74:77], v[58:61]
	v_mfma_f32_16x16x32_bf16 v[38:41], v[84:87], v[78:81], v[38:41]
	ds_read2_b64 v[84:87], v90 offset0:232 offset1:236
	s_waitcnt lgkmcnt(0)
	v_mov_b32_e32 v88, v84
	v_mov_b32_e32 v89, v85
	s_nop 1
	v_mfma_f32_16x16x32_bf16 v[54:57], v[86:89], v[74:77], v[54:57]
	ds_read2_b64 v[74:77], v91 offset0:136 offset1:140
	s_waitcnt lgkmcnt(0)
	v_mfma_f32_16x16x32_bf16 v[62:65], v[74:77], v[66:69], v[62:65]
	v_mfma_f32_16x16x32_bf16 v[46:49], v[74:77], v[70:73], v[46:49]
	ds_read2_b64 v[74:77], v92 offset0:168 offset1:172
	v_mfma_f32_16x16x32_bf16 v[34:37], v[86:89], v[78:81], v[34:37]
	s_waitcnt lgkmcnt(0)
	v_mov_b32_e32 v78, v74
	v_mov_b32_e32 v79, v75
	s_nop 1
	v_mfma_f32_16x16x32_bf16 v[50:53], v[76:79], v[66:69], v[50:53]
	v_mfma_f32_16x16x32_bf16 v[42:45], v[76:79], v[70:73], v[42:45]
	ds_read2_b64 v[74:77], v93 offset0:192 offset1:196
	s_waitcnt lgkmcnt(0)
	v_mfma_f32_16x16x32_bf16 v[58:61], v[74:77], v[66:69], v[58:61]
	v_mfma_f32_16x16x32_bf16 v[38:41], v[74:77], v[70:73], v[38:41]
	ds_read2_b64 v[74:77], v90 offset0:224 offset1:228
	s_waitcnt lgkmcnt(0)
	v_mov_b32_e32 v78, v74
	v_mov_b32_e32 v79, v75
	s_nop 1
	v_mfma_f32_16x16x32_bf16 v[54:57], v[76:79], v[66:69], v[54:57]
	v_mfma_f32_16x16x32_bf16 v[34:37], v[76:79], v[70:73], v[34:37]
	s_setprio 0
	s_branch .LBB0_760

.LBB0_773:
	s_setprio 3
	s_cmp_lt_i32 s35, 1
	s_cbranch_scc1 .LBB0_776
	s_xor_b32 s6, s26, 1
	s_mulk_i32 s6, 0x4800
	v_lshl_or_b32 v0, v96, 1, s6
	v_add_u32_e32 v66, s6, v152
	v_add_u32_e32 v67, v0, v158
	s_waitcnt vmcnt(3)
	ds_write_b128 v67, v[10:13]
	v_lshl_add_u32 v67, v159, 1, v66
	v_add_u32_e32 v0, v0, v161
	s_waitcnt vmcnt(2)
	ds_write_b16 v67, v22 offset:9216
	ds_write_b16_d16_hi v67, v22 offset:9360
	ds_write_b16 v67, v23 offset:9504
	ds_write_b16_d16_hi v67, v23 offset:9648
	ds_write_b16 v67, v24 offset:9792
	ds_write_b16_d16_hi v67, v24 offset:9936
	ds_write_b16 v67, v25 offset:10080
	ds_write_b16_d16_hi v67, v25 offset:10224
	s_waitcnt vmcnt(1)
	ds_write_b128 v0, v[26:29]
	v_lshl_add_u32 v0, v162, 1, v66
	s_cmp_eq_u32 s35, 1
	s_waitcnt vmcnt(0)
	ds_write_b16 v0, v30 offset:9216
	ds_write_b16_d16_hi v0, v30 offset:9360
	ds_write_b16 v0, v31 offset:9504
	ds_write_b16_d16_hi v0, v31 offset:9648
	ds_write_b16 v0, v32 offset:9792
	ds_write_b16_d16_hi v0, v32 offset:9936
	ds_write_b16 v0, v33 offset:10080
	ds_write_b16_d16_hi v0, v33 offset:10224
	s_cbranch_scc1 .LBB0_776
	s_movk_i32 s10, 0x1800
	v_mad_i64_i32 v[10:11], s[6:7], v167, s10, v[104:105]
	s_mov_b64 s[12:13], 0x800
	v_mad_i64_i32 v[26:27], s[6:7], v103, s10, v[104:105]
	v_lshl_add_u64 v[22:23], v[10:11], 0, s[12:13]
	v_lshl_add_u64 v[30:31], v[26:27], 0, s[12:13]
	global_load_dwordx4 v[10:13], v[10:11], off offset:2048
	s_nop 0
	global_load_dwordx4 v[22:25], v[22:23], off offset:2048
	s_nop 0
	global_load_dwordx4 v[26:29], v[26:27], off offset:2048
	s_nop 0
	global_load_dwordx4 v[30:33], v[30:31], off offset:2048
.LBB0_776:
	s_setprio 0
	v_cmp_le_i32_e32 vcc, s35, v101
	s_xor_b64 s[6:7], s[38:39], -1
	s_and_b64 s[10:11], vcc, s[6:7]
	s_and_saveexec_b64 s[6:7], s[10:11]
	s_cbranch_execz .LBB0_778
	s_mul_i32 s10, s26, 0x4800
	v_add_u32_e32 v169, s10, v154
	v_add_u32_e32 v0, v169, v153
	ds_read_b128 v[66:69], v0
	ds_read_b128 v[74:77], v0 offset:64
	ds_read_b128 v[78:81], v0 offset:2304
	ds_read_b128 v[82:85], v0 offset:2368
	ds_read_b128 v[90:93], v0 offset:4608
	ds_read_b128 v[108:111], v0 offset:4672
	ds_read_b128 v[116:119], v0 offset:6912
	ds_read_b128 v[120:123], v0 offset:6976
	s_waitcnt vmcnt(3) lgkmcnt(7)
	s_setprio 2
	v_mfma_f32_16x16x32_bf16 v[70:73], v[66:69], v[2:5], 0
	v_cmp_lt_i32_e32 vcc, v184, v182
	s_mov_b32 s30, 0x3f317218
	v_mov_b32_e32 v214, v1
	s_waitcnt vmcnt(2) lgkmcnt(6)
	v_mfma_f32_16x16x32_bf16 v[130:133], v[74:77], v[6:9], v[70:73]
	v_cndmask_b32_e32 v0, v180, v184, vcc
	v_lshlrev_b32_e32 v204, 2, v0
	v_cmp_lt_i32_e32 vcc, v183, v182
	s_waitcnt lgkmcnt(1)
	v_mfma_f32_16x16x32_bf16 v[126:129], v[116:119], v[2:5], 0
	v_mov_b32_e32 v216, v1
	s_nop 1
	v_mul_f32_e32 v70, 0x3e000000, v130
	v_mul_f32_e64 v71, |v70|, s41
	v_exp_f32_e32 v71, v71
	v_max_f32_e32 v70, 0, v70
	v_cndmask_b32_e32 v72, v180, v183, vcc
	v_mfma_f32_16x16x32_bf16 v[112:115], v[90:93], v[2:5], 0
	v_add_f32_e32 v0, 1.0, v71
	v_log_f32_e32 v0, v0
	v_lshlrev_b32_e32 v203, 2, v72
	s_waitcnt vmcnt(1)
	v_mfma_f32_16x16x32_bf16 v[134:137], v[90:93], v[14:17], 0
	v_cmp_ne_u32_e32 vcc, 0, v168
	v_fmac_f32_e32 v70, 0x3f317218, v0
	v_mul_f32_e32 v0, 0x3e000000, v131
	v_fma_f32 v145, v130, s4, -v70
	v_add_f32_e32 v212, 0, v70
	v_mul_f32_e64 v90, |v0|, s41
	s_waitcnt lgkmcnt(0)
	v_mfma_f32_16x16x32_bf16 v[70:73], v[120:123], v[6:9], v[126:129]
	v_max_f32_e32 v0, 0, v0
	s_or_b64 s[10:11], s[48:49], vcc
	s_or_b64 s[94:95], s[56:57], vcc
	v_mfma_f32_16x16x32_bf16 v[86:89], v[78:81], v[2:5], 0
	v_exp_f32_e32 v126, v90
	s_nop 2
	v_mul_f32_e32 v127, 0x3e000000, v70
	s_or_b64 s[16:17], s[64:65], vcc
	v_mfma_f32_16x16x32_bf16 v[78:81], v[78:81], v[14:17], 0
	v_add_f32_e32 v126, 1.0, v126
	s_or_b64 s[14:15], s[54:55], vcc
	s_or_b64 s[18:19], s[68:69], vcc
	v_mfma_f32_16x16x32_bf16 v[90:93], v[82:85], v[6:9], v[86:89]
	s_or_b64 s[96:97], s[58:59], vcc
	v_cndmask_b32_e64 v226, v193, v145, s[94:95]
	s_or_b64 s[98:99], s[62:63], vcc
	v_mul_f32_e64 v86, |v127|, s41
	v_exp_f32_e32 v128, v86
	v_mfma_f32_16x16x32_bf16 v[86:89], v[108:111], v[6:9], v[112:115]
	v_mov_b32_e32 v145, v1
	s_or_b64 s[20:21], s[80:81], vcc
	s_or_b64 s[22:23], s[84:85], vcc
	v_log_f32_e32 v112, v126
	s_waitcnt vmcnt(0)
	v_mfma_f32_16x16x32_bf16 v[82:85], v[82:85], v[18:21], v[78:81]
	v_add_f32_e32 v113, 1.0, v128
	v_log_f32_e32 v113, v113
	v_fmac_f32_e32 v0, 0x3f317218, v112
	v_mfma_f32_16x16x32_bf16 v[78:81], v[108:111], v[18:21], v[134:137]
	v_mul_f32_e32 v109, 0x3e000000, v132
	v_mul_f32_e64 v110, |v109|, s41
	v_exp_f32_e32 v110, v110
	v_cndmask_b32_e64 v108, 0, v0, s[10:11]
	v_fma_f32 v0, v131, s4, -v0
	v_mul_f32_e32 v111, 0x3e000000, v133
	v_cndmask_b32_e64 v205, v193, v0, s[10:11]
	v_max_f32_e32 v0, 0, v109
	v_add_f32_e32 v109, 1.0, v110
	v_mul_f32_e64 v110, |v111|, s41
	v_log_f32_e32 v109, v109
	v_exp_f32_e32 v112, v110
	s_or_b64 s[10:11], s[50:51], vcc
	v_max_f32_e32 v114, 0, v127
	v_fmac_f32_e32 v0, 0x3f317218, v109
	v_add_f32_e32 v109, 1.0, v112
	v_log_f32_e32 v109, v109
	v_cndmask_b32_e64 v110, 0, v0, s[10:11]
	v_fma_f32 v0, v132, s4, -v0
	v_cndmask_b32_e64 v206, v193, v0, s[10:11]
	v_max_f32_e32 v0, 0, v111
	v_fmac_f32_e32 v0, 0x3f317218, v109
	v_mul_f32_e32 v109, 0x3e000000, v90
	v_mul_f32_e64 v111, |v109|, s41
	v_exp_f32_e32 v111, v111
	s_or_b64 s[10:11], s[52:53], vcc
	v_cndmask_b32_e64 v112, 0, v0, s[10:11]
	v_fma_f32 v0, v133, s4, -v0
	v_cndmask_b32_e64 v207, v193, v0, s[10:11]
	v_add_f32_e32 v0, 1.0, v111
	v_mul_f32_e32 v111, 0x3e000000, v91
	v_mfma_f32_16x16x32_bf16 v[66:69], v[66:69], v[14:17], 0
	v_fmac_f32_e32 v114, 0x3f317218, v113
	v_mul_f32_e64 v113, |v111|, s41
	v_log_f32_e32 v0, v0
	v_mfma_f32_16x16x32_bf16 v[116:119], v[116:119], v[14:17], 0
	v_exp_f32_e32 v113, v113
	s_or_b64 s[10:11], s[60:61], vcc
	v_cndmask_b32_e64 v132, 0, v212, s[94:95]
	v_mfma_f32_16x16x32_bf16 v[66:69], v[74:77], v[18:21], v[66:69]
	v_mov_b32_e32 v212, v1
	s_or_b64 s[12:13], s[86:87], vcc
	s_or_b64 s[24:25], s[88:89], vcc
	v_mfma_f32_16x16x32_bf16 v[74:77], v[120:123], v[18:21], v[116:119]
	s_setprio 0
	v_fma_f32 v70, v70, s4, -v114
	v_cndmask_b32_e32 v70, v193, v70, vcc
	s_nop 0
	v_max_f32_e32 v118, 0, v109
	v_fmac_f32_e32 v118, 0x3f317218, v0
	v_add_f32_e32 v0, 1.0, v113
	v_mul_f32_e32 v113, 0x3e000000, v92
	v_log_f32_e32 v109, v0
	v_mul_f32_e64 v0, |v113|, s41
	v_exp_f32_e32 v115, v0
	v_max_f32_e32 v0, 0, v111
	v_mul_f32_e32 v148, 0x3f317218, v109
	v_max_f32_e32 v150, 0, v113
	v_add_f32_e32 v109, 1.0, v115
	v_log_f32_e32 v196, v109
	v_mul_f32_e32 v109, 0x3e000000, v93
	v_mul_f32_e64 v111, |v109|, s41
	v_mul_f32_e32 v113, 0x3e000000, v86
	v_exp_f32_e32 v111, v111
	v_mul_f32_e64 v115, |v113|, s41
	v_exp_f32_e32 v115, v115
	v_max_f32_e32 v198, 0, v109
	v_add_f32_e32 v109, 1.0, v111
	v_log_f32_e32 v210, v109
	v_add_f32_e32 v109, 1.0, v115
	v_mul_f32_e32 v111, 0x3e000000, v87
	v_log_f32_e32 v109, v109
	v_mul_f32_e64 v115, |v111|, s41
	v_exp_f32_e32 v115, v115
	v_max_f32_e32 v134, 0, v113
	v_fmac_f32_e32 v134, 0x3f317218, v109
	v_mul_f32_e32 v109, 0x3e000000, v88
	v_fma_f32 v113, v86, s4, -v134
	v_add_f32_e32 v86, 1.0, v115
	v_mul_f32_e64 v115, |v109|, s41
	v_log_f32_e32 v86, v86
	v_exp_f32_e32 v115, v115
	v_max_f32_e32 v144, 0, v111
	v_max_f32_e32 v138, 0, v109
	v_mul_f32_e32 v146, 0x3f317218, v86
	v_add_f32_e32 v86, 1.0, v115
	v_log_f32_e32 v142, v86
	v_mul_f32_e32 v86, 0x3e000000, v89
	v_mul_f32_e64 v109, |v86|, s41
	v_mul_f32_e32 v111, 0x3e000000, v71
	v_exp_f32_e32 v109, v109
	v_mul_f32_e64 v115, |v111|, s41
	v_exp_f32_e32 v115, v115
	v_max_f32_e32 v136, 0, v86
	v_add_f32_e32 v86, 1.0, v109
	v_log_f32_e32 v140, v86
	v_add_f32_e32 v86, 1.0, v115
	v_mul_f32_e32 v115, 0x3e000000, v72
	v_log_f32_e32 v109, v86
	v_mul_f32_e64 v86, |v115|, s41
	v_exp_f32_e32 v116, v86
	v_max_f32_e32 v86, 0, v111
	v_mul_f32_e32 v111, 0x3e000000, v66
	v_max_f32_e32 v120, 0, v115
	v_mul_f32_e64 v115, |v111|, s41
	v_exp_f32_e32 v115, v115
	v_mul_f32_e32 v126, 0x3f317218, v109
	v_add_f32_e32 v109, 1.0, v116
	v_log_f32_e32 v122, v109
	v_mul_f32_e32 v109, 0x3e000000, v73
	v_mul_f32_e64 v116, |v109|, s41
	v_max_f32_e32 v128, 0, v109
	v_add_f32_e32 v109, 1.0, v115
	v_exp_f32_e32 v116, v116
	v_log_f32_e32 v109, v109
	v_max_f32_e32 v111, 0, v111
	v_fma_f32 v90, v90, s4, -v118
	v_add_f32_e32 v115, 1.0, v116
	v_fmac_f32_e32 v111, 0x3f317218, v109
	v_mul_f32_e32 v109, 0x3e000000, v67
	v_log_f32_e32 v130, v115
	v_mul_f32_e64 v115, |v109|, s41
	v_exp_f32_e32 v115, v115
	v_fma_f32 v208, v66, s4, -v111
	v_add_f32_e32 v133, 0, v111
	v_mul_f32_e32 v111, 0x3e000000, v68
	v_add_f32_e32 v66, 1.0, v115
	v_log_f32_e32 v66, v66
	v_mul_f32_e64 v115, |v111|, s41
	v_exp_f32_e32 v115, v115
	v_max_f32_e32 v109, 0, v109
	v_fmac_f32_e32 v109, 0x3f317218, v66
	v_fma_f32 v209, v67, s4, -v109
	v_add_f32_e32 v67, 1.0, v115
	v_log_f32_e32 v116, v67
	v_mul_f32_e32 v67, 0x3e000000, v69
	v_max_f32_e32 v66, 0, v111
	v_mul_f32_e64 v111, |v67|, s41
	v_mul_f32_e32 v115, 0x3e000000, v82
	v_exp_f32_e32 v111, v111
	v_mul_f32_e64 v117, |v115|, s41
	v_exp_f32_e32 v119, v117
	v_max_f32_e32 v149, 0, v115
	v_add_f32_e32 v111, 1.0, v111
	v_log_f32_e32 v117, v111
	v_add_f32_e32 v111, 1.0, v119
	v_mul_f32_e32 v119, 0x3e000000, v83
	v_mul_f32_e64 v121, |v119|, s41
	v_log_f32_e32 v111, v111
	v_exp_f32_e32 v121, v121
	v_mul_f32_e32 v115, 0x3e000000, v84
	v_max_f32_e32 v213, 0, v119
	v_fmac_f32_e32 v149, 0x3f317218, v111
	v_add_f32_e32 v111, 1.0, v121
	v_mul_f32_e64 v121, |v115|, s41
	v_log_f32_e32 v111, v111
	v_exp_f32_e32 v121, v121
	v_max_f32_e32 v151, 0, v115
	v_fma_f32 v82, v82, s4, -v149
	v_mul_f32_e32 v119, 0x3f317218, v111
	v_add_f32_e32 v111, 1.0, v121
	v_log_f32_e32 v197, v111
	v_mul_f32_e32 v111, 0x3e000000, v85
	v_mul_f32_e64 v115, |v111|, s41
	v_mul_f32_e32 v121, 0x3e000000, v78
	v_exp_f32_e32 v115, v115
	v_mul_f32_e64 v123, |v121|, s41
	v_exp_f32_e32 v123, v123
	v_max_f32_e32 v199, 0, v111
	v_add_f32_e32 v111, 1.0, v115
	v_mul_f32_e32 v115, 0x3e000000, v79
	v_log_f32_e32 v211, v111
	v_add_f32_e32 v111, 1.0, v123
	v_mul_f32_e64 v123, |v115|, s41
	v_log_f32_e32 v111, v111
	v_exp_f32_e32 v123, v123
	v_max_f32_e32 v147, 0, v121
	v_mul_f32_e32 v121, 0x3e000000, v80
	v_fmac_f32_e32 v147, 0x3f317218, v111
	v_add_f32_e32 v111, 1.0, v123
	v_mul_f32_e64 v123, |v121|, s41
	v_log_f32_e32 v111, v111
	v_exp_f32_e32 v123, v123
	v_max_f32_e32 v215, 0, v115
	v_max_f32_e32 v139, 0, v121
	v_mul_f32_e32 v135, 0x3f317218, v111
	v_add_f32_e32 v111, 1.0, v123
	v_log_f32_e32 v143, v111
	v_mul_f32_e32 v111, 0x3e000000, v81
	v_mul_f32_e64 v115, |v111|, s41
	v_mul_f32_e32 v121, 0x3e000000, v74
	v_exp_f32_e32 v115, v115
	v_mul_f32_e64 v123, |v121|, s41
	v_exp_f32_e32 v123, v123
	v_max_f32_e32 v137, 0, v111
	v_add_f32_e32 v111, 1.0, v115
	v_mul_f32_e32 v115, 0x3e000000, v75
	v_log_f32_e32 v141, v111
	v_add_f32_e32 v111, 1.0, v123
	v_mul_f32_e64 v123, |v115|, s41
	v_log_f32_e32 v111, v111
	v_exp_f32_e32 v123, v123
	v_max_f32_e32 v127, 0, v121
	v_max_f32_e32 v217, 0, v115
	v_fmac_f32_e32 v127, 0x3f317218, v111
	v_add_f32_e32 v111, 1.0, v123
	v_log_f32_e32 v111, v111
	v_pk_add_f32 v[218:219], v[0:1], v[148:149]
	v_pk_fma_f32 v[148:149], v[196:197], s[30:31], v[150:151] op_sel_hi:[1,0,1]
	v_pk_fma_f32 v[150:151], v[210:211], s[30:31], v[198:199] op_sel_hi:[1,0,1]
	v_mul_f32_e32 v115, 0x3f317218, v111
	v_mul_f32_e32 v111, 0x3e000000, v76
	v_mul_f32_e64 v121, |v111|, s41
	v_exp_f32_e32 v123, v121
	v_max_f32_e32 v121, 0, v111
	v_mul_f32_e32 v111, 0x3e000000, v77
	v_mul_f32_e64 v129, |v111|, s41
	v_exp_f32_e32 v131, v129
	v_max_f32_e32 v129, 0, v111
	v_pk_add_f32 v[198:199], v[212:213], v[118:119]
	v_fma_f32 v0, v91, s4, -v218
	v_add_f32_e32 v111, 1.0, v131
	v_log_f32_e32 v131, v111
	v_cndmask_b32_e64 v111, v193, v90, s[10:11]
	v_fma_f32 v90, v92, s4, -v148
	v_cndmask_b32_e64 v227, v193, v90, s[16:17]
	v_fma_f32 v90, v93, s4, -v150
	v_cndmask_b32_e64 v228, v193, v90, s[18:19]
	v_cndmask_b32_e64 v197, 0, v219, s[94:95]
	v_cndmask_b32_e64 v196, 0, v218, s[14:15]
	v_cndmask_b32_e64 v91, 0, v199, s[96:97]
	v_cndmask_b32_e64 v90, 0, v198, s[10:11]
	v_pk_add_f32 v[118:119], v[196:197], v[90:91]
	v_cndmask_b32_e64 v93, 0, v149, s[98:99]
	v_cndmask_b32_e64 v92, 0, v148, s[16:17]
	v_pk_add_f32 v[144:145], v[144:145], v[146:147]
	v_pk_add_f32 v[210:211], v[92:93], v[118:119]
	v_cndmask_b32_e64 v118, 0, v150, s[18:19]
	s_or_b64 s[18:19], s[76:77], vcc
	v_fma_f32 v87, v87, s4, -v144
	s_or_b64 s[16:17], s[72:73], vcc
	v_fma_f32 v78, v78, s4, -v147
	v_cndmask_b32_e64 v0, v193, v0, s[14:15]
	v_cndmask_b32_e64 v90, v193, v113, s[18:19]
	v_cndmask_b32_e64 v113, v193, v87, s[16:17]
	v_pk_fma_f32 v[142:143], v[142:143], s[30:31], v[138:139] op_sel_hi:[1,0,1]
	s_or_b64 s[14:15], s[70:71], vcc
	v_cndmask_b32_e64 v144, 0, v144, s[16:17]
	v_pk_add_f32 v[146:147], v[214:215], v[134:135]
	s_or_b64 s[16:17], s[74:75], vcc
	s_or_b64 s[10:11], s[66:67], vcc
	v_fma_f32 v87, v88, s4, -v142
	v_pk_fma_f32 v[140:141], v[140:141], s[30:31], v[136:137] op_sel_hi:[1,0,1]
	v_cndmask_b32_e64 v145, 0, v145, s[14:15]
	v_cndmask_b32_e64 v135, 0, v147, s[16:17]
	v_cndmask_b32_e64 v134, 0, v146, s[18:19]
	s_or_b64 s[18:19], s[78:79], vcc
	v_cndmask_b32_e64 v119, 0, v151, s[10:11]
	v_cndmask_b32_e64 v148, v193, v87, s[20:21]
	v_fma_f32 v87, v89, s4, -v140
	v_pk_add_f32 v[88:89], v[144:145], v[134:135]
	v_cndmask_b32_e64 v137, 0, v143, s[18:19]
	v_cndmask_b32_e64 v136, 0, v142, s[20:21]
	s_or_b64 s[20:21], s[82:83], vcc
	v_pk_add_f32 v[210:211], v[118:119], v[210:211]
	v_pk_add_f32 v[88:89], v[136:137], v[88:89]
	v_cndmask_b32_e64 v139, 0, v141, s[20:21]
	v_cndmask_b32_e64 v138, 0, v140, s[22:23]
	ds_bpermute_b32 v212, v204, v210
	ds_bpermute_b32 v213, v204, v211
	v_pk_add_f32 v[88:89], v[138:139], v[88:89]
	ds_bpermute_b32 v214, v204, v88
	ds_bpermute_b32 v215, v204, v89
	v_add_f32_e32 v123, 1.0, v123
	s_waitcnt lgkmcnt(2)
	v_pk_add_f32 v[210:211], v[210:211], v[212:213]
	ds_bpermute_b32 v218, v203, v210
	v_log_f32_e32 v123, v123
	s_waitcnt lgkmcnt(1)
	v_pk_add_f32 v[220:221], v[88:89], v[214:215]
	ds_bpermute_b32 v222, v203, v220
	v_cndmask_b32_e64 v150, v193, v87, s[22:23]
	v_cndmask_b32_e64 v87, 0, v212, s[44:45]
	s_waitcnt lgkmcnt(1)
	v_cndmask_b32_e64 v88, 0, v218, s[46:47]
	v_add_f32_e32 v134, v87, v88
	v_cndmask_b32_e64 v87, 0, v214, s[44:45]
	s_waitcnt lgkmcnt(0)
	v_cndmask_b32_e64 v88, 0, v222, s[46:47]
	v_add_f32_e32 v140, v87, v88
	v_mov_b32_e32 v87, v1
	v_fma_f32 v74, v74, s4, -v127
	v_pk_add_f32 v[86:87], v[86:87], v[126:127]
	v_pk_fma_f32 v[126:127], v[130:131], s[30:31], v[128:129] op_sel_hi:[1,0,1]
	v_pk_add_f32 v[130:131], v[216:217], v[114:115]
	v_cndmask_b32_e64 v74, v193, v74, s[12:13]
	v_pk_fma_f32 v[122:123], v[122:123], s[30:31], v[120:121] op_sel_hi:[1,0,1]
	v_cndmask_b32_e64 v129, 0, v87, s[12:13]
	v_cndmask_b32_e32 v128, 0, v86, vcc
	v_cndmask_b32_e64 v89, 0, v131, s[24:25]
	v_cndmask_b32_e32 v88, 0, v130, vcc
	s_or_b64 s[12:13], s[90:91], vcc
	v_pk_add_f32 v[120:121], v[128:129], v[88:89]
	v_cndmask_b32_e64 v115, 0, v123, s[12:13]
	v_cndmask_b32_e32 v114, 0, v122, vcc
	s_or_b64 s[22:23], s[92:93], vcc
	v_pk_add_f32 v[216:217], v[114:115], v[120:121]
	v_cndmask_b32_e64 v121, 0, v127, s[22:23]
	v_cndmask_b32_e32 v120, 0, v126, vcc
	v_pk_add_f32 v[216:217], v[120:121], v[216:217]
	ds_bpermute_b32 v224, v204, v216
	ds_bpermute_b32 v225, v204, v217
	v_fma_f32 v71, v71, s4, -v86
	ds_bpermute_b32 v219, v203, v211
	ds_bpermute_b32 v223, v203, v221
	v_fma_f32 v72, v72, s4, -v122
	s_waitcnt lgkmcnt(2)
	v_pk_add_f32 v[86:87], v[216:217], v[224:225]
	ds_bpermute_b32 v216, v203, v86
	ds_bpermute_b32 v217, v203, v87
	v_cndmask_b32_e32 v88, v193, v72, vcc
	v_fma_f32 v72, v73, s4, -v126
	v_cndmask_b32_e32 v122, v193, v72, vcc
	v_cndmask_b32_e64 v72, 0, v224, s[44:45]
	s_waitcnt lgkmcnt(1)
	v_cndmask_b32_e64 v73, 0, v216, s[46:47]
	s_waitcnt lgkmcnt(0)
	v_pk_add_f32 v[86:87], v[86:87], v[216:217]
	v_add_f32_e32 v126, v72, v73
	v_pk_add_f32 v[72:73], v[210:211], v[218:219]
	v_pk_add_f32 v[210:211], v[220:221], v[222:223]
	v_pk_add_f32 v[220:221], v[106:107], v[86:87]
	v_add_f32_e32 v106, v106, v126
	v_pk_add_f32 v[210:211], v[210:211], v[220:221]
	v_add_f32_e32 v120, v120, v106
	v_pk_add_f32 v[86:87], v[72:73], v[210:211]
	v_add_f32_e32 v72, v134, v210
	v_add_f32_e32 v73, v118, v72
	v_add_f32_e32 v92, v92, v73
	v_add_f32_e32 v118, v196, v92
	v_sub_f32_e32 v0, v0, v92
	v_sub_f32_e32 v92, v111, v118
	v_add_f32_e32 v111, v140, v220
	v_add_f32_e32 v118, v138, v111
	v_sub_f32_e32 v72, v228, v72
	v_sub_f32_e32 v73, v227, v73
	v_add_f32_e32 v129, v136, v118
	v_sub_f32_e32 v106, v122, v106
	v_sub_f32_e32 v88, v88, v120
	v_mul_f32_e32 v72, 0x3fb8aa3b, v72
	v_mul_f32_e32 v73, 0x3fb8aa3b, v73
	v_mul_f32_e32 v0, 0x3fb8aa3b, v0
	v_mul_f32_e32 v92, 0x3fb8aa3b, v92
	v_add_f32_e32 v130, v144, v129
	v_mul_f32_e32 v106, 0x3fb8aa3b, v106
	v_mul_f32_e32 v88, 0x3fb8aa3b, v88
	v_exp_f32_e32 v72, v72
	v_exp_f32_e32 v73, v73
	v_exp_f32_e32 v0, v0
	v_exp_f32_e32 v92, v92
	v_sub_f32_e32 v113, v113, v129
	v_sub_f32_e32 v90, v90, v130
	v_exp_f32_e32 v106, v106
	v_exp_f32_e32 v88, v88
	v_mul_f32_e32 v113, 0x3fb8aa3b, v113
	v_mul_f32_e32 v90, 0x3fb8aa3b, v90
	v_add_f32_e32 v114, v114, v120
	v_cndmask_b32_e32 v71, v193, v71, vcc
	v_sub_f32_e32 v111, v150, v111
	v_sub_f32_e32 v118, v148, v118
	v_exp_f32_e32 v113, v113
	v_exp_f32_e32 v90, v90
	v_add_f32_e32 v126, v128, v114
	v_mul_f32_e32 v111, 0x3fb8aa3b, v111
	v_mul_f32_e32 v118, 0x3fb8aa3b, v118
	v_sub_f32_e32 v71, v71, v114
	v_sub_f32_e32 v70, v70, v126
	v_exp_f32_e32 v111, v111
	v_exp_f32_e32 v118, v118
	v_mul_f32_e32 v71, 0x3fb8aa3b, v71
	v_mul_f32_e32 v70, 0x3fb8aa3b, v70
	v_cvt_pk_bf16_f32 v128, v92, v0
	v_cvt_pk_bf16_f32 v129, v73, v72
	v_cvt_pk_bf16_f32 v73, v88, v106
	v_cndmask_b32_e64 v0, v193, v82, s[94:95]
	v_fma_f32 v82, v83, s4, -v199
	v_fma_f32 v83, v84, s4, -v149
	v_fma_f32 v84, v85, s4, -v151
	v_cndmask_b32_e64 v85, 0, v213, s[44:45]
	v_cndmask_b32_e64 v88, 0, v219, s[46:47]
	v_exp_f32_e32 v114, v71
	v_exp_f32_e32 v120, v70
	v_add_f32_e32 v85, v85, v88
	v_cndmask_b32_e64 v88, v193, v78, s[14:15]
	v_fma_f32 v78, v79, s4, -v147
	v_max_f32_e32 v67, 0, v67
	v_cvt_pk_bf16_f32 v70, v90, v113
	v_cndmask_b32_e64 v90, v193, v78, s[16:17]
	v_fma_f32 v78, v80, s4, -v143
	v_cndmask_b32_e64 v92, v193, v78, s[18:19]
	v_fma_f32 v78, v81, s4, -v141
	v_pk_fma_f32 v[66:67], v[116:117], s[30:31], v[66:67] op_sel_hi:[1,0,1]
	v_pk_add_f32 v[132:133], v[108:109], v[132:133]
	v_cvt_pk_bf16_f32 v71, v118, v111
	v_cndmask_b32_e64 v106, v193, v78, s[20:21]
	v_cndmask_b32_e64 v78, 0, v215, s[44:45]
	v_cndmask_b32_e64 v79, 0, v223, s[46:47]
	v_mov_b32_e32 v111, v66
	v_cvt_pk_bf16_f32 v72, v120, v114
	v_add_f32_e32 v114, v78, v79
	v_pk_add_f32 v[78:79], v[110:111], v[132:133]
	v_mov_b32_e32 v113, v67
	v_pk_add_f32 v[78:79], v[112:113], v[78:79]
	ds_bpermute_b32 v80, v204, v78
	ds_bpermute_b32 v81, v204, v79
	v_fma_f32 v76, v76, s4, -v123
	v_cndmask_b32_e64 v111, v193, v76, s[12:13]
	v_fma_f32 v76, v77, s4, -v127
	v_cndmask_b32_e64 v113, v193, v76, s[22:23]
	s_waitcnt lgkmcnt(0)
	v_pk_add_f32 v[116:117], v[78:79], v[80:81]
	ds_bpermute_b32 v122, v203, v116
	v_cndmask_b32_e64 v76, 0, v225, s[44:45]
	v_cndmask_b32_e64 v77, 0, v217, s[46:47]
	v_add_f32_e32 v76, v76, v77
	v_cndmask_b32_e64 v77, 0, v80, s[44:45]
	s_waitcnt lgkmcnt(0)
	v_cndmask_b32_e64 v78, 0, v122, s[46:47]
	v_add_f32_e32 v77, v77, v78
	v_add_f32_e32 v77, v77, v86
	v_add_f32_e32 v78, v112, v77
	v_add_f32_e32 v79, v110, v78
	v_sub_f32_e32 v77, v207, v77
	v_sub_f32_e32 v78, v206, v78
	v_mul_f32_e32 v77, 0x3fb8aa3b, v77
	v_mul_f32_e32 v78, 0x3fb8aa3b, v78
	ds_bpermute_b32 v123, v203, v117
	v_exp_f32_e32 v77, v77
	v_exp_f32_e32 v78, v78
	v_add_f32_e32 v80, v108, v79
	v_sub_f32_e32 v79, v205, v79
	v_sub_f32_e32 v80, v226, v80
	v_cvt_pk_bf16_f32 v127, v78, v77
	v_cndmask_b32_e64 v77, 0, v81, s[44:45]
	s_waitcnt lgkmcnt(0)
	v_cndmask_b32_e64 v78, 0, v123, s[46:47]
	v_add_f32_e32 v77, v77, v78
	v_add_f32_e32 v77, v77, v87
	v_mul_f32_e32 v79, 0x3fb8aa3b, v79
	v_mul_f32_e32 v80, 0x3fb8aa3b, v80
	v_fma_f32 v69, v69, s4, -v67
	v_add_f32_e32 v67, v77, v67
	v_exp_f32_e32 v79, v79
	v_exp_f32_e32 v80, v80
	v_add_f32_e32 v78, v66, v67
	v_fma_f32 v66, v68, s4, -v66
	v_sub_f32_e32 v66, v66, v67
	v_mul_f32_e32 v66, 0x3fb8aa3b, v66
	v_exp_f32_e32 v108, v66
	v_sub_f32_e32 v66, v209, v78
	v_cvt_pk_bf16_f32 v126, v80, v79
	v_add_f32_e32 v79, v109, v78
	v_mul_f32_e32 v66, 0x3fb8aa3b, v66
	v_exp_f32_e32 v78, v66
	v_sub_f32_e32 v66, v208, v79
	v_mul_f32_e32 v66, 0x3fb8aa3b, v66
	v_cndmask_b32_e64 v84, v193, v84, s[10:11]
	v_exp_f32_e32 v79, v66
	v_add_f32_e32 v66, v85, v211
	v_add_f32_e32 v67, v119, v66
	v_sub_f32_e32 v66, v84, v66
	v_cndmask_b32_e64 v83, v193, v83, s[98:99]
	v_mul_f32_e32 v66, 0x3fb8aa3b, v66
	v_exp_f32_e32 v84, v66
	v_sub_f32_e32 v66, v83, v67
	v_cndmask_b32_e64 v82, v193, v82, s[96:97]
	v_add_f32_e32 v68, v93, v67
	v_mul_f32_e32 v66, 0x3fb8aa3b, v66
	v_sub_f32_e32 v69, v69, v77
	v_exp_f32_e32 v85, v66
	v_sub_f32_e32 v66, v82, v68
	v_mul_f32_e32 v69, 0x3fb8aa3b, v69
	v_mul_f32_e32 v66, 0x3fb8aa3b, v66
	v_exp_f32_e32 v77, v69
	v_add_f32_e32 v69, v91, v68
	v_exp_f32_e32 v91, v66
	v_add_f32_e32 v66, v114, v221
	v_add_f32_e32 v67, v139, v66
	v_sub_f32_e32 v66, v106, v66
	v_mul_f32_e32 v66, 0x3fb8aa3b, v66
	v_exp_f32_e32 v93, v66
	v_sub_f32_e32 v66, v92, v67
	v_add_f32_e32 v68, v137, v67
	v_mul_f32_e32 v66, 0x3fb8aa3b, v66
	v_exp_f32_e32 v92, v66
	v_sub_f32_e32 v66, v90, v68
	v_sub_f32_e32 v0, v0, v69
	v_add_f32_e32 v69, v135, v68
	v_mul_f32_e32 v66, 0x3fb8aa3b, v66
	v_exp_f32_e32 v90, v66
	v_sub_f32_e32 v66, v88, v69
	v_lshl_add_u32 v88, v155, 1, v169
	v_add_u32_e32 v106, 0x2000, v88
	v_mul_f32_e32 v80, 0x3fb8aa3b, v66
	ds_read2_b64 v[66:69], v106 offset0:128 offset1:132
	v_add_u32_e32 v110, 0x2800, v88
	v_exp_f32_e32 v109, v80
	ds_read2_b64 v[80:83], v110 offset0:160 offset1:164
	v_mul_f32_e32 v0, 0x3fb8aa3b, v0
	v_exp_f32_e32 v0, v0
	v_add_f32_e32 v107, v107, v76
	v_cvt_pk_bf16_f32 v76, v79, v78
	v_cvt_pk_bf16_f32 v79, v85, v84
	s_waitcnt lgkmcnt(0)
	v_mov_b32_e32 v84, v80
	v_mov_b32_e32 v85, v81
	v_cvt_pk_bf16_f32 v77, v108, v77
	v_cvt_pk_bf16_f32 v78, v0, v91
	v_add_u32_e32 v108, 0x3000, v88
	s_setprio 2
	v_mfma_f32_16x16x32_bf16 v[62:65], v[66:69], v[126:129], v[62:65]
	v_sub_f32_e32 v80, v113, v107
	v_add_u32_e32 v88, 0x3800, v88
	v_add_f32_e32 v0, v121, v107
	v_mfma_f32_16x16x32_bf16 v[54:57], v[66:69], v[76:79], v[54:57]
	ds_read2_b64 v[66:69], v108 offset0:200 offset1:204
	v_mul_f32_e32 v107, 0x3fb8aa3b, v80
	v_fma_f32 v75, v75, s4, -v131
	v_mfma_f32_16x16x32_bf16 v[58:61], v[82:85], v[126:129], v[58:61]
	v_add_f32_e32 v91, v115, v0
	v_cndmask_b32_e64 v75, v193, v75, s[24:25]
	v_add_f32_e32 v89, v89, v91
	v_mfma_f32_16x16x32_bf16 v[46:49], v[82:85], v[76:79], v[46:49]
	ds_read2_b64 v[80:83], v88 offset0:232 offset1:236
	v_sub_f32_e32 v0, v111, v0
	v_sub_f32_e32 v75, v75, v91
	s_waitcnt lgkmcnt(1)
	v_mfma_f32_16x16x32_bf16 v[50:53], v[66:69], v[126:129], v[50:53]
	v_sub_f32_e32 v74, v74, v89
	s_waitcnt lgkmcnt(0)
	v_mov_b32_e32 v84, v80
	v_mov_b32_e32 v85, v81
	v_mfma_f32_16x16x32_bf16 v[42:45], v[66:69], v[76:79], v[42:45]
	ds_read2_b64 v[66:69], v106 offset0:136 offset1:140
	v_mul_f32_e32 v0, 0x3fb8aa3b, v0
	v_mul_f32_e32 v75, 0x3fb8aa3b, v75
	v_mul_f32_e32 v74, 0x3fb8aa3b, v74
	v_exp_f32_e32 v107, v107
	v_exp_f32_e32 v0, v0
	v_exp_f32_e32 v91, v75
	v_mfma_f32_16x16x32_bf16 v[34:37], v[82:85], v[76:79], v[34:37]
	v_exp_f32_e32 v76, v74
	ds_read2_b64 v[78:81], v110 offset0:168 offset1:172
	v_cvt_pk_bf16_f32 v74, v109, v90
	v_cvt_pk_bf16_f32 v75, v92, v93
	v_cvt_pk_bf16_f32 v76, v76, v91
	v_cvt_pk_bf16_f32 v77, v0, v107
	s_waitcnt lgkmcnt(1)
	v_mfma_f32_16x16x32_bf16 v[62:65], v[66:69], v[70:73], v[62:65]
	s_mov_b32 s10, 0x42b40000
	s_mov_b32 s97, 0x27c0000
	s_mov_b32 s96, 0x800000
	v_mfma_f32_16x16x32_bf16 v[54:57], v[66:69], v[74:77], v[54:57]
	s_waitcnt lgkmcnt(0)
	v_mov_b32_e32 v66, v80
	v_mov_b32_e32 v67, v81
	v_mov_b32_e32 v68, v78
	v_mov_b32_e32 v69, v79
	ds_read2_b64 v[78:81], v88 offset0:224 offset1:228
	v_mfma_f32_16x16x32_bf16 v[38:41], v[82:85], v[126:129], v[38:41]
	s_mov_b32 s30, 0x27e0000
	v_mfma_f32_16x16x32_bf16 v[58:61], v[66:69], v[70:73], v[58:61]
	v_mfma_f32_16x16x32_bf16 v[46:49], v[66:69], v[74:77], v[46:49]
	ds_read2_b64 v[66:69], v108 offset0:192 offset1:196
	s_waitcnt lgkmcnt(0)
	v_mfma_f32_16x16x32_bf16 v[50:53], v[66:69], v[70:73], v[50:53]
	v_mfma_f32_16x16x32_bf16 v[42:45], v[66:69], v[74:77], v[42:45]
	v_mov_b32_e32 v66, v80
	v_mov_b32_e32 v67, v81
	v_mov_b32_e32 v68, v78
	v_mov_b32_e32 v69, v79
	s_nop 1
	v_mfma_f32_16x16x32_bf16 v[38:41], v[66:69], v[70:73], v[38:41]
	v_add_f32_e64 v70, v116, v122
	v_add_f32_e64 v71, v117, v123
	v_pk_add_f32 v[106:107], v[70:71], v[86:87]
	v_mfma_f32_16x16x32_bf16 v[34:37], v[66:69], v[74:77], v[34:37]
	s_setprio 0
	v_cmp_lt_f32_e32 vcc, s10, v106
	v_cmp_lt_f32_e64 s[10:11], s10, v107
	s_and_b64 s[10:11], vcc, s[10:11]
	s_nop 0
	v_cndmask_b32_e64 v0, 0, 1, s[10:11]
	v_cmp_ne_u32_e32 vcc, 0, v0
	s_cmp_eq_u64 vcc, exec
	s_cselect_b64 s[10:11], -1, 0
	s_andn2_b64 s[12:13], s[38:39], exec
	s_and_b64 s[10:11], s[10:11], exec
	s_or_b64 s[38:39], s[12:13], s[10:11]
